# attention unit prologue: drop the vmcnt(0) before the tile loop, the loop-top counted wait covers Q and tile 0 (prologue de-serialisation)
# baseline (speedup 1.0000x reference)
; #define LAS __attribute__((address_space(3)))
; #define GAS __attribute__((address_space(1)))
; __device__ __forceinline__ void unit(const Ctx& F, int b, int h, int qb, const bf16_t* Q, const bf16_t* Kg, const bf16_t* VT, bf16_t* O, float lam) {
;     LAS unsigned char* lds = F.lds; const int lane = F.lane, wid = F.wave, r32 = lane & 31, hi = lane >> 5, rg = wid >> 1, s = wid & 1;
;     const size_t tok0 = (size_t)b * SEQ; const int q0 = qb * 128 + rg * 32;
;     bf16x8 qf[4];
;     { const bf16_t* qp = Q + (tok0 + q0 + r32) * D + h * 128 + s * 64 + hi * 8;
; #pragma unroll
;       for (int d0 = 0; d0 < 4; ++d0) qf[d0] = *(const GAS bf16x8*)(qp + d0 * 16); }
;     f32x16 o[4];
; #pragma unroll
;     for (int db = 0; db < 4; ++db)
; #pragma unroll
;         for (int r = 0; r < 16; ++r) o[db][r] = 0.f;
;     float mrun = -1e30f, lrun = 0.f;
;     const int NT = qb * 2 + 2, cq = qb * 2 + (rg >> 1);
;     const bf16_t* ksrc[2]; const bf16_t* vsrc[2];
; #pragma unroll
;     for (int i = 0; i < 2; ++i) { const int kr = 4 * (2 * wid + i) + (lane >> 4), ks = (lane & 15) ^ (kr & 15); ksrc[i] = Kg + (tok0 + kr) * D + h * 128 + ks * 8;
;         const int vr = 8 * (2 * wid + i) + (lane >> 3), vs = (lane & 7) ^ ((vr >> 1) & 7); vsrc[i] = VT + (size_t)(h * 128 + vr) * T + tok0 + vs * 8; }
;     ...
;     ATT_DMA(0, 0); ATT_DMA(1, BUF);
.LBB0_234:
	s_lshr_b32 s15, s34, 6
	s_and_b32 s16, s42, 4
	s_add_i32 s16, s16, s15
	s_and_b32 s15, s16, 7
	s_lshl_b32 s74, s15, 8
	s_lshl_b32 s45, s15, 7
	s_lshl_b32 s15, s43, 1
	s_and_b32 s15, s15, 12
	s_or_b32 s15, s15, s35
	s_add_i32 s15, s15, s36
	s_bitcmp0_b32 s43, 0
	s_cselect_b32 s75, s40, s41
	s_ashr_i32 s26, s15, 3
	s_lshl_b32 s16, s75, 7
	s_ashr_i32 s27, s26, 31
	s_add_i32 s16, s16, s8
	s_lshl_b64 s[50:51], s[26:27], 11
	s_ashr_i32 s17, s16, 31
	s_add_u32 s16, s50, s16
	s_addc_u32 s17, s51, s17
	v_mov_b32_e32 v1, s17
	v_or_b32_e32 v0, s16, v112
	s_lshl_b32 s15, s15, 7
	v_lshlrev_b64 v[0:1], 11, v[0:1]
	s_and_b32 s44, s15, 0x380
	v_lshl_add_u64 v[0:1], s[24:25], 0, v[0:1]
	s_lshl_b32 s52, s44, 1
	s_mov_b32 s53, s88
	v_lshl_add_u64 v[0:1], v[0:1], 0, s[52:53]
	s_mov_b32 s15, s88
	v_lshl_add_u64 v[0:1], v[0:1], 0, s[14:15]
	s_lshl_b32 s15, s75, 1
	v_lshl_add_u64 v[0:1], v[0:1], 0, v[156:157]
	s_add_u32 s52, s0, s52
	global_load_dwordx4 v[96:99], v[0:1], off
	global_load_dwordx4 v[100:103], v[0:1], off offset:32
	global_load_dwordx4 v[104:107], v[0:1], off offset:64
	global_load_dwordx4 v[108:111], v[0:1], off offset:96
	s_addc_u32 s53, s1, 0
	s_lshl_b64 s[54:55], s[26:27], 12
	v_lshl_add_u64 v[0:1], s[50:51], 0, v[114:115]
	v_add_u32_e32 v2, s44, v165
	s_add_u32 s72, s4, s54
	v_lshlrev_b64 v[0:1], 11, v[0:1]
	v_ashrrev_i32_e32 v3, 31, v2
	s_addc_u32 s73, s5, s55
	v_lshl_add_u64 v[0:1], s[52:53], 0, v[0:1]
	v_mov_b32_e32 v145, v157
	v_lshlrev_b64 v[2:3], 16, v[2:3]
	v_lshl_add_u64 v[4:5], s[50:51], 0, v[116:117]
	v_add_u32_e32 v6, s44, v172
	s_mov_b32 m0, s28
	v_lshl_add_u64 v[0:1], v[0:1], 0, v[144:145]
	v_lshl_add_u64 v[2:3], s[72:73], 0, v[2:3]
	v_mov_b32_e32 v147, v157
	v_lshlrev_b64 v[4:5], 11, v[4:5]
	v_ashrrev_i32_e32 v7, 31, v6
	v_lshl_add_u64 v[2:3], v[2:3], 0, v[146:147]
	v_lshl_add_u64 v[4:5], s[52:53], 0, v[4:5]
	v_mov_b32_e32 v149, v157
	v_lshlrev_b64 v[6:7], 16, v[6:7]
	global_load_lds_dwordx4 v[0:1], off
	s_add_i32 m0, s28, 0x4000
	v_lshl_add_u64 v[4:5], v[4:5], 0, v[148:149]
	v_lshl_add_u64 v[6:7], s[72:73], 0, v[6:7]
	v_mov_b32_e32 v151, v157
	global_load_lds_dwordx4 v[2:3], off
	s_add_i32 m0, s28, 0x400
	v_lshl_add_u64 v[6:7], v[6:7], 0, v[150:151]
	global_load_lds_dwordx4 v[4:5], off
	s_mov_b32 m0, s29
	v_lshl_add_u64 v[0:1], v[0:1], 0, s[18:19]
	global_load_lds_dwordx4 v[6:7], off
	s_add_i32 m0, s28, 0x8000
	s_lshl_b64 s[26:27], s[26:27], 22
	global_load_lds_dwordx4 v[0:1], off
	v_lshl_add_u64 v[0:1], v[2:3], 0, s[38:39]
	s_add_i32 m0, s28, 0xc000
	v_add_u32_e32 v2, s45, v165
	global_load_lds_dwordx4 v[0:1], off
	v_lshl_add_u64 v[0:1], v[4:5], 0, s[18:19]
	s_mov_b32 m0, s30
	v_ashrrev_i32_e32 v3, 31, v2
	global_load_lds_dwordx4 v[0:1], off
	v_lshl_add_u64 v[0:1], v[6:7], 0, s[38:39]
	s_mov_b32 m0, s31
	v_lshlrev_b64 v[2:3], 16, v[2:3]
	global_load_lds_dwordx4 v[0:1], off
	v_add_u32_e32 v0, s45, v183
	v_ashrrev_i32_e32 v1, 31, v0
	v_lshlrev_b64 v[0:1], 16, v[0:1]
	v_lshl_add_u64 v[0:1], v[136:137], 0, v[0:1]
	v_lshl_add_u64 v[154:155], v[0:1], 0, s[54:55]
	v_lshl_add_u64 v[0:1], v[138:139], 0, v[2:3]
	v_mov_b32_e32 v48, v157
	v_mov_b32_e32 v49, v157
	s_lshl_b32 s53, s75, 16
	s_or_b32 s26, s26, s74
	v_lshl_add_u64 v[168:169], v[0:1], 0, s[54:55]
	v_mov_b32_e32 v50, v157
	v_mov_b32_e32 v51, v157
	v_mov_b32_e32 v52, v157
	v_mov_b32_e32 v53, v157
	v_mov_b32_e32 v54, v157
	v_mov_b32_e32 v55, v157
	v_mov_b32_e32 v56, v157
	v_mov_b32_e32 v57, v157
	v_mov_b32_e32 v58, v157
	v_mov_b32_e32 v59, v157
	v_mov_b32_e32 v60, v157
	v_mov_b32_e32 v61, v157
	v_mov_b32_e32 v62, v157
	v_mov_b32_e32 v63, v157
	v_mov_b64_e32 v[32:33], v[48:49]
	v_mov_b64_e32 v[16:17], v[48:49]
	v_mov_b64_e32 v[0:1], v[48:49]
	s_mov_b32 s45, 1
	s_mov_b32 s50, 2
	s_add_i32 s51, s15, 2
	s_add_i32 s52, s15, s9
	s_add_i32 s53, s53, 0x10000
	v_lshl_add_u64 v[152:153], s[26:27], 0, v[134:135]
	v_lshl_add_u64 v[170:171], s[26:27], 0, v[140:141]
	v_mov_b32_e32 v143, 0
	v_mov_b32_e32 v145, 0xf149f2ca
	s_mov_b32 s54, 0
	v_mov_b64_e32 v[34:35], v[50:51]
	v_mov_b64_e32 v[36:37], v[52:53]
	v_mov_b64_e32 v[38:39], v[54:55]
	v_mov_b64_e32 v[40:41], v[56:57]
	v_mov_b64_e32 v[42:43], v[58:59]
	v_mov_b64_e32 v[44:45], v[60:61]
	v_mov_b64_e32 v[46:47], v[62:63]
	v_mov_b64_e32 v[18:19], v[50:51]
	v_mov_b64_e32 v[20:21], v[52:53]
	v_mov_b64_e32 v[22:23], v[54:55]
	v_mov_b64_e32 v[24:25], v[56:57]
	v_mov_b64_e32 v[26:27], v[58:59]
	v_mov_b64_e32 v[28:29], v[60:61]
	v_mov_b64_e32 v[30:31], v[62:63]
	v_mov_b64_e32 v[2:3], v[50:51]
	v_mov_b64_e32 v[4:5], v[52:53]
	v_mov_b64_e32 v[6:7], v[54:55]
	v_mov_b64_e32 v[8:9], v[56:57]
	v_mov_b64_e32 v[10:11], v[58:59]
	v_mov_b64_e32 v[12:13], v[60:61]
	v_mov_b64_e32 v[14:15], v[62:63]
	s_mov_b32 s55, 0
	s_branch .LBB0_237
